# split barrier A: arrival posted at the second tile's epilogue entry without waits or barriers; leader test and flush after that epilogue
# speedup vs baseline: 1.0140x; 1.0082x over previous
.LBB0_241:
	s_cmp_eq_u32 s8, 2
	s_cbranch_scc0 .Lsb_a2_skip
	s_and_saveexec_b64 s[100:101], s[56:57]
	s_cbranch_execz .Lsb_a2_x
	v_mov_b32_e32 v246, 0x20ff0
	ds_read_b32 v246, v246
	s_waitcnt vmcnt(16) lgkmcnt(0)
	v_add_u32_e32 v247, 1, v247
	v_cmp_eq_u32_e32 vcc, v247, v246
	s_cbranch_vccz .Lsb_a2_x
	buffer_wbl2 sc1
	s_waitcnt vmcnt(0)
	v_readlane_b32 s98, v242, 47
	s_nop 3
	s_cmp_eq_u32 s98, 0
	s_cselect_b32 s98, 0, 8
	s_add_u32 s98, s98, 0x16370d00
	s_add_u32 s98, s68, s98
	s_addc_u32 s99, s69, 0
	v_mov_b32_e32 v246, 0
	v_mov_b32_e32 v247, 1
	global_atomic_add v246, v247, s[98:99]
	s_waitcnt vmcnt(0)

.LBB0_248:
	s_cmp_eq_u32 s8, 2
	s_cbranch_scc0 .Lsb_a1_skip
	s_and_saveexec_b64 s[100:101], s[56:57]
	s_cbranch_execz .Lsb_a1_x
	v_readlane_b32 s98, v242, 47
	s_nop 3
	s_cmp_eq_u32 s98, 0
	s_cselect_b32 s99, 0, 128
	s_getreg_b32 s98, hwreg(HW_REG_XCC_ID, 0, 4)
	s_lshl_b32 s98, s98, 2
	s_add_u32 s98, s98, s99
	s_add_u32 s98, s98, 0x16370e00
	s_add_u32 s98, s68, s98
	s_addc_u32 s99, s69, 0
	v_mov_b32_e32 v246, 0
	v_mov_b32_e32 v247, 1
	global_atomic_add v247, v246, v247, s[98:99] sc0
.Lsb_a1_x:
	s_or_b64 exec, exec, s[100:101]
.Lsb_a1_skip:
	v_lshl_or_b32 v172, s10, 8, v190
	v_lshl_add_u32 v168, s9, 8, v189
	v_ashrrev_i32_e32 v173, 31, v172
	v_ashrrev_i32_e32 v169, 31, v168
	v_lshl_add_u64 v[60:61], v[172:173], 2, s[46:47]
	v_lshl_add_u64 v[166:167], v[168:169], 2, s[44:45]
	global_load_dwordx4 v[64:67], v[60:61], off offset:16
	global_load_dwordx4 v[68:71], v[60:61], off
	global_load_dwordx4 v[56:59], v[60:61], off offset:528
	s_nop 0
	global_load_dwordx4 v[60:63], v[60:61], off offset:512
	v_lshlrev_b64 v[172:173], 1, v[172:173]
	global_load_dword v200, v[166:167], off
	global_load_dword v201, v[166:167], off offset:64
	global_load_dword v202, v[166:167], off offset:128
	global_load_dword v203, v[166:167], off offset:192
	global_load_dword v204, v[166:167], off offset:512
	global_load_dword v205, v[166:167], off offset:576
	global_load_dword v206, v[166:167], off offset:640
	global_load_dword v207, v[166:167], off offset:704
	s_waitcnt vmcnt(0)
	v_fmamk_f32 v169, v200, 0x3a000000, v176
	v_readlane_b32 s10, v244, 4
	v_readlane_b32 s11, v244, 5
	v_rsq_f32_e32 v174, v169
	s_nop 0
	v_mov_b64_e32 v[170:171], s[10:11]
	v_mad_i64_i32 v[192:193], s[10:11], v168, s62, v[170:171]
	v_lshl_add_u64 v[192:193], v[192:193], 0, v[172:173]
	v_pk_fma_f32 v[142:143], v[142:143], v[174:175], v[70:71] op_sel_hi:[1,0,1]
	v_pk_fma_f32 v[140:141], v[140:141], v[174:175], v[68:69] op_sel_hi:[1,0,1]
	v_pk_fma_f32 v[194:195], v[138:139], v[174:175], v[66:67] op_sel_hi:[1,0,1]
	v_pk_fma_f32 v[138:139], v[136:137], v[174:175], v[64:65] op_sel_hi:[1,0,1]
	v_cvt_pk_bf16_f32 v136, v140, v141
	v_cvt_pk_bf16_f32 v137, v142, v143
	v_pk_fma_f32 v[134:135], v[134:135], v[174:175], v[62:63] op_sel_hi:[1,0,1]
	v_cvt_pk_bf16_f32 v138, v138, v139
	v_cvt_pk_bf16_f32 v139, v194, v195
	global_store_dwordx4 v[192:193], v[136:139], off
	v_pk_fma_f32 v[132:133], v[132:133], v[174:175], v[60:61] op_sel_hi:[1,0,1]
	s_nop 0
	v_pk_fma_f32 v[136:137], v[130:131], v[174:175], v[58:59] op_sel_hi:[1,0,1]
	v_pk_fma_f32 v[130:131], v[128:129], v[174:175], v[56:57] op_sel_hi:[1,0,1]
	v_cvt_pk_bf16_f32 v128, v132, v133
	v_cvt_pk_bf16_f32 v129, v134, v135
	s_nop 0
	v_cvt_pk_bf16_f32 v130, v130, v131
	v_cvt_pk_bf16_f32 v131, v136, v137
	global_store_dwordx4 v[192:193], v[128:131], off offset:256
	s_nop 0
	s_nop 0
	v_or_b32_e32 v129, 16, v168
	v_fmamk_f32 v128, v201, 0x3a000000, v176
	v_rsq_f32_e32 v128, v128
	v_mad_i64_i32 v[130:131], s[10:11], v129, s62, v[170:171]
	v_lshl_add_u64 v[130:131], v[130:131], 0, v[172:173]
	v_pk_fma_f32 v[126:127], v[126:127], v[128:129], v[70:71] op_sel_hi:[1,0,1]
	v_pk_fma_f32 v[124:125], v[124:125], v[128:129], v[68:69] op_sel_hi:[1,0,1]
	v_pk_fma_f32 v[132:133], v[122:123], v[128:129], v[66:67] op_sel_hi:[1,0,1]
	v_pk_fma_f32 v[122:123], v[120:121], v[128:129], v[64:65] op_sel_hi:[1,0,1]
	v_cvt_pk_bf16_f32 v120, v124, v125
	v_cvt_pk_bf16_f32 v121, v126, v127
	v_pk_fma_f32 v[118:119], v[118:119], v[128:129], v[62:63] op_sel_hi:[1,0,1]
	v_cvt_pk_bf16_f32 v122, v122, v123
	v_cvt_pk_bf16_f32 v123, v132, v133
	global_store_dwordx4 v[130:131], v[120:123], off
	v_pk_fma_f32 v[116:117], v[116:117], v[128:129], v[60:61] op_sel_hi:[1,0,1]
	s_nop 0
	v_pk_fma_f32 v[120:121], v[114:115], v[128:129], v[58:59] op_sel_hi:[1,0,1]
	v_pk_fma_f32 v[114:115], v[112:113], v[128:129], v[56:57] op_sel_hi:[1,0,1]
	v_cvt_pk_bf16_f32 v112, v116, v117
	v_cvt_pk_bf16_f32 v113, v118, v119
	s_nop 0
	v_cvt_pk_bf16_f32 v114, v114, v115
	v_cvt_pk_bf16_f32 v115, v120, v121
	global_store_dwordx4 v[130:131], v[112:115], off offset:256
	s_nop 0
	s_nop 0
	v_or_b32_e32 v113, 32, v168
	v_fmamk_f32 v112, v202, 0x3a000000, v176
	v_rsq_f32_e32 v112, v112
	v_mad_i64_i32 v[114:115], s[10:11], v113, s62, v[170:171]
	v_lshl_add_u64 v[114:115], v[114:115], 0, v[172:173]
	v_pk_fma_f32 v[110:111], v[110:111], v[112:113], v[70:71] op_sel_hi:[1,0,1]
	v_pk_fma_f32 v[108:109], v[108:109], v[112:113], v[68:69] op_sel_hi:[1,0,1]
	v_pk_fma_f32 v[116:117], v[106:107], v[112:113], v[66:67] op_sel_hi:[1,0,1]
	v_pk_fma_f32 v[106:107], v[104:105], v[112:113], v[64:65] op_sel_hi:[1,0,1]
	v_cvt_pk_bf16_f32 v104, v108, v109
	v_cvt_pk_bf16_f32 v105, v110, v111
	v_pk_fma_f32 v[102:103], v[102:103], v[112:113], v[62:63] op_sel_hi:[1,0,1]
	v_cvt_pk_bf16_f32 v106, v106, v107
	v_cvt_pk_bf16_f32 v107, v116, v117
	global_store_dwordx4 v[114:115], v[104:107], off
	v_pk_fma_f32 v[100:101], v[100:101], v[112:113], v[60:61] op_sel_hi:[1,0,1]
	s_nop 0
	v_pk_fma_f32 v[104:105], v[98:99], v[112:113], v[58:59] op_sel_hi:[1,0,1]
	v_pk_fma_f32 v[98:99], v[96:97], v[112:113], v[56:57] op_sel_hi:[1,0,1]
	v_cvt_pk_bf16_f32 v96, v100, v101
	v_cvt_pk_bf16_f32 v97, v102, v103
	s_nop 0
	v_cvt_pk_bf16_f32 v98, v98, v99
	v_cvt_pk_bf16_f32 v99, v104, v105
	global_store_dwordx4 v[114:115], v[96:99], off offset:256
	s_nop 0
	s_nop 0
	v_or_b32_e32 v97, 48, v168
	v_fmamk_f32 v96, v203, 0x3a000000, v176
	v_rsq_f32_e32 v96, v96
	v_mad_i64_i32 v[98:99], s[10:11], v97, s62, v[170:171]
	v_lshl_add_u64 v[98:99], v[98:99], 0, v[172:173]
	v_pk_fma_f32 v[94:95], v[94:95], v[96:97], v[70:71] op_sel_hi:[1,0,1]
	v_pk_fma_f32 v[92:93], v[92:93], v[96:97], v[68:69] op_sel_hi:[1,0,1]
	v_pk_fma_f32 v[100:101], v[90:91], v[96:97], v[66:67] op_sel_hi:[1,0,1]
	v_pk_fma_f32 v[90:91], v[88:89], v[96:97], v[64:65] op_sel_hi:[1,0,1]
	v_cvt_pk_bf16_f32 v88, v92, v93
	v_cvt_pk_bf16_f32 v89, v94, v95
	v_pk_fma_f32 v[86:87], v[86:87], v[96:97], v[62:63] op_sel_hi:[1,0,1]
	v_cvt_pk_bf16_f32 v90, v90, v91
	v_cvt_pk_bf16_f32 v91, v100, v101
	global_store_dwordx4 v[98:99], v[88:91], off
	v_pk_fma_f32 v[84:85], v[84:85], v[96:97], v[60:61] op_sel_hi:[1,0,1]
	s_nop 0
	v_pk_fma_f32 v[88:89], v[82:83], v[96:97], v[58:59] op_sel_hi:[1,0,1]
	v_pk_fma_f32 v[82:83], v[80:81], v[96:97], v[56:57] op_sel_hi:[1,0,1]
	v_cvt_pk_bf16_f32 v80, v84, v85
	v_cvt_pk_bf16_f32 v81, v86, v87
	s_nop 0
	v_cvt_pk_bf16_f32 v82, v82, v83
	v_cvt_pk_bf16_f32 v83, v88, v89
	global_store_dwordx4 v[98:99], v[80:83], off offset:256
	s_nop 0
	s_nop 0
	v_add_u32_e32 v81, 0x80, v168
	v_fmamk_f32 v80, v204, 0x3a000000, v176
	v_rsq_f32_e32 v80, v80
	v_mad_i64_i32 v[82:83], s[10:11], v81, s62, v[170:171]
	v_lshl_add_u64 v[82:83], v[82:83], 0, v[172:173]
	v_pk_fma_f32 v[78:79], v[78:79], v[80:81], v[70:71] op_sel_hi:[1,0,1]
	v_pk_fma_f32 v[76:77], v[76:77], v[80:81], v[68:69] op_sel_hi:[1,0,1]
	v_pk_fma_f32 v[84:85], v[74:75], v[80:81], v[66:67] op_sel_hi:[1,0,1]
	v_pk_fma_f32 v[74:75], v[72:73], v[80:81], v[64:65] op_sel_hi:[1,0,1]
	v_cvt_pk_bf16_f32 v72, v76, v77
	v_cvt_pk_bf16_f32 v73, v78, v79
	v_pk_fma_f32 v[54:55], v[54:55], v[80:81], v[62:63] op_sel_hi:[1,0,1]
	v_cvt_pk_bf16_f32 v74, v74, v75
	v_cvt_pk_bf16_f32 v75, v84, v85
	global_store_dwordx4 v[82:83], v[72:75], off
	v_pk_fma_f32 v[52:53], v[52:53], v[80:81], v[60:61] op_sel_hi:[1,0,1]
	s_nop 0
	v_pk_fma_f32 v[72:73], v[50:51], v[80:81], v[58:59] op_sel_hi:[1,0,1]
	v_pk_fma_f32 v[50:51], v[48:49], v[80:81], v[56:57] op_sel_hi:[1,0,1]
	v_cvt_pk_bf16_f32 v48, v52, v53
	v_cvt_pk_bf16_f32 v49, v54, v55
	s_nop 0
	v_cvt_pk_bf16_f32 v50, v50, v51
	v_cvt_pk_bf16_f32 v51, v72, v73
	global_store_dwordx4 v[82:83], v[48:51], off offset:256
	s_nop 0
	s_nop 0
	v_add_u32_e32 v49, 0x90, v168
	v_fmamk_f32 v48, v205, 0x3a000000, v176
	v_rsq_f32_e32 v48, v48
	v_mad_i64_i32 v[50:51], s[10:11], v49, s62, v[170:171]
	v_lshl_add_u64 v[50:51], v[50:51], 0, v[172:173]
	v_pk_fma_f32 v[46:47], v[46:47], v[48:49], v[70:71] op_sel_hi:[1,0,1]
	v_pk_fma_f32 v[44:45], v[44:45], v[48:49], v[68:69] op_sel_hi:[1,0,1]
	v_pk_fma_f32 v[52:53], v[42:43], v[48:49], v[66:67] op_sel_hi:[1,0,1]
	v_pk_fma_f32 v[42:43], v[40:41], v[48:49], v[64:65] op_sel_hi:[1,0,1]
	v_cvt_pk_bf16_f32 v40, v44, v45
	v_cvt_pk_bf16_f32 v41, v46, v47
	v_pk_fma_f32 v[38:39], v[38:39], v[48:49], v[62:63] op_sel_hi:[1,0,1]
	v_cvt_pk_bf16_f32 v42, v42, v43
	v_cvt_pk_bf16_f32 v43, v52, v53
	global_store_dwordx4 v[50:51], v[40:43], off
	v_pk_fma_f32 v[36:37], v[36:37], v[48:49], v[60:61] op_sel_hi:[1,0,1]
	s_nop 0
	v_pk_fma_f32 v[40:41], v[34:35], v[48:49], v[58:59] op_sel_hi:[1,0,1]
	v_pk_fma_f32 v[34:35], v[32:33], v[48:49], v[56:57] op_sel_hi:[1,0,1]
	v_cvt_pk_bf16_f32 v32, v36, v37
	v_cvt_pk_bf16_f32 v33, v38, v39
	s_nop 0
	v_cvt_pk_bf16_f32 v34, v34, v35
	v_cvt_pk_bf16_f32 v35, v40, v41
	global_store_dwordx4 v[50:51], v[32:35], off offset:256
	s_nop 0
	s_nop 0
	v_add_u32_e32 v33, 0xa0, v168
	v_fmamk_f32 v32, v206, 0x3a000000, v176
	v_rsq_f32_e32 v32, v32
	v_mad_i64_i32 v[34:35], s[10:11], v33, s62, v[170:171]
	v_lshl_add_u64 v[34:35], v[34:35], 0, v[172:173]
	v_pk_fma_f32 v[30:31], v[30:31], v[32:33], v[70:71] op_sel_hi:[1,0,1]
	v_pk_fma_f32 v[28:29], v[28:29], v[32:33], v[68:69] op_sel_hi:[1,0,1]
	v_pk_fma_f32 v[36:37], v[26:27], v[32:33], v[66:67] op_sel_hi:[1,0,1]
	v_pk_fma_f32 v[26:27], v[24:25], v[32:33], v[64:65] op_sel_hi:[1,0,1]
	v_cvt_pk_bf16_f32 v24, v28, v29
	v_cvt_pk_bf16_f32 v25, v30, v31
	v_pk_fma_f32 v[22:23], v[22:23], v[32:33], v[62:63] op_sel_hi:[1,0,1]
	v_cvt_pk_bf16_f32 v26, v26, v27
	v_cvt_pk_bf16_f32 v27, v36, v37
	global_store_dwordx4 v[34:35], v[24:27], off
	v_pk_fma_f32 v[20:21], v[20:21], v[32:33], v[60:61] op_sel_hi:[1,0,1]
	s_nop 0
	v_pk_fma_f32 v[24:25], v[18:19], v[32:33], v[58:59] op_sel_hi:[1,0,1]
	v_pk_fma_f32 v[18:19], v[16:17], v[32:33], v[56:57] op_sel_hi:[1,0,1]
	v_cvt_pk_bf16_f32 v16, v20, v21
	v_cvt_pk_bf16_f32 v17, v22, v23
	s_nop 0
	v_cvt_pk_bf16_f32 v18, v18, v19
	v_cvt_pk_bf16_f32 v19, v24, v25
	global_store_dwordx4 v[34:35], v[16:19], off offset:256
	s_nop 0
	s_nop 0
	v_add_u32_e32 v17, 0xb0, v168
	v_fmamk_f32 v16, v207, 0x3a000000, v176
	s_mov_b64 s[42:43], -1
	v_rsq_f32_e32 v16, v16
	v_mad_i64_i32 v[18:19], s[10:11], v17, s62, v[170:171]
	v_lshl_add_u64 v[18:19], v[18:19], 0, v[172:173]
	v_pk_fma_f32 v[14:15], v[14:15], v[16:17], v[70:71] op_sel_hi:[1,0,1]
	v_pk_fma_f32 v[12:13], v[12:13], v[16:17], v[68:69] op_sel_hi:[1,0,1]
	v_pk_fma_f32 v[20:21], v[10:11], v[16:17], v[66:67] op_sel_hi:[1,0,1]
	v_pk_fma_f32 v[10:11], v[8:9], v[16:17], v[64:65] op_sel_hi:[1,0,1]
	v_cvt_pk_bf16_f32 v8, v12, v13
	v_cvt_pk_bf16_f32 v9, v14, v15
	s_andn2_b64 vcc, exec, s[40:41]
	v_cvt_pk_bf16_f32 v10, v10, v11
	v_cvt_pk_bf16_f32 v11, v20, v21
	global_store_dwordx4 v[18:19], v[8:11], off
	v_pk_fma_f32 v[6:7], v[6:7], v[16:17], v[62:63] op_sel_hi:[1,0,1]
	v_pk_fma_f32 v[4:5], v[4:5], v[16:17], v[60:61] op_sel_hi:[1,0,1]
	v_pk_fma_f32 v[8:9], v[2:3], v[16:17], v[58:59] op_sel_hi:[1,0,1]
	v_pk_fma_f32 v[2:3], v[0:1], v[16:17], v[56:57] op_sel_hi:[1,0,1]
	v_cvt_pk_bf16_f32 v0, v4, v5
	v_cvt_pk_bf16_f32 v1, v6, v7
	s_nop 0
	v_cvt_pk_bf16_f32 v2, v2, v3
	v_cvt_pk_bf16_f32 v3, v8, v9
	global_store_dwordx4 v[18:19], v[0:3], off offset:256
	s_cbranch_vccnz .LBB0_241
	s_andn2_b64 vcc, exec, s[0:1]
	s_cbranch_vccnz .LBB0_240
	s_barrier
	s_branch .LBB0_240
